# gdn_prep: touch the token's four input rows up front (the per-token loads were a serial load-wait chain)
# speedup vs baseline: 1.0718x; 1.0031x over previous
; __device__ __forceinline__ void unpack8(v4u c, float (&f)[8]) { f[0] = bflo(c.x); f[1] = bfhi(c.x); f[2] = bflo(c.y); f[3] = bfhi(c.y); f[4] = bflo(c.z); f[5] = bfhi(c.z); f[6] = bflo(c.w); f[7] = bfhi(c.w); }
; __device__ __forceinline__ void phase_gdn_prep(Ctx& C, int i) {
;     ...
;     for (int tile = C.bid; tile < M / 8; tile += C.G) {
;         const int m = tile * 8 + wave; const bool prompt = m < MP;
;         const int t = prompt ? (m & (TP - 1)) : ((m - MP) & 7); const int b = prompt ? (m >> 11) : ((m - MP) >> 3);
;         const bool last = prompt ? (t == TP - 1) : (t == 7);
;         const bf16* P = PG + (size_t)m * GPR;
;         const float* cs = C.in[5] + ((size_t)i * SB + (prompt ? 0 : b)) * 3 * GQKV;
;         float* go = prompt ? C.out + O_GC_P + ((size_t)i * NB + b) * 3 * GQKV : C.out + O_GC_S + ((size_t)i * SB + b) * 3 * GQKV;
;     ...
;         for (int blk = 0; blk < 3; ++blk) {
;             const int col0 = blk * 512 + lane * 8;
;             float xr[4][8];
;             unpack8(*(const v4u*)(P + col0), xr[0]);
; #pragma unroll
;             for (int j = 1; j < 4; ++j) {
;                 if (t - j >= 0) unpack8(*(const v4u*)(P - (size_t)j * GPR + col0), xr[j]);
;                 else if (prompt) {
; #pragma unroll
;                     for (int e = 0; e < 8; ++e) xr[j][e] = 0.f; }
;                 else { const f32x4 a = *(const f32x4*)(cs + (3 + t - j) * GQKV + col0), c4 = *(const f32x4*)(cs + (3 + t - j) * GQKV + col0 + 4);
;                     xr[j][0] = a.x; xr[j][1] = a.y; xr[j][2] = a.z; xr[j][3] = a.w; xr[j][4] = c4.x; xr[j][5] = c4.y; xr[j][6] = c4.z; xr[j][7] = c4.w; }
;             }
.LBB0_805:
	s_and_b32 s41, s50, 0x7ff
	s_and_b64 s[34:35], s[42:43], exec
	s_cselect_b32 s60, s41, s2
	s_cselect_b32 s40, 0, s40
	s_lshl_b64 s[34:35], s[50:51], 12
	v_lshl_add_u64 v[18:19], v[10:11], 0, s[34:35]
	global_load_dwordx4 v[242:245], v[18:19], off offset:1024
	global_load_dwordx4 v[242:245], v[18:19], off offset:2048
	global_load_dwordx4 v[242:245], v[18:19], off offset:3072
	global_load_dwordx4 v[242:245], v[18:19], off offset:-4096
	global_load_dwordx4 v[242:245], v[18:19], off offset:-3072
	global_load_dwordx4 v[242:245], v[18:19], off offset:-2048
	global_load_dwordx4 v[242:245], v[18:19], off offset:-1024
	s_mov_b32 s34, 0xffffe000
	s_mov_b32 s35, -1
	v_lshl_add_u64 v[246:247], v[18:19], 0, s[34:35]
	global_load_dwordx4 v[242:245], v[246:247], off
	global_load_dwordx4 v[242:245], v[246:247], off offset:1024
	global_load_dwordx4 v[242:245], v[246:247], off offset:2048
	global_load_dwordx4 v[242:245], v[246:247], off offset:3072
	global_load_dwordx4 v[242:245], v[246:247], off offset:-4096
	global_load_dwordx4 v[242:245], v[246:247], off offset:-3072
	global_load_dwordx4 v[242:245], v[246:247], off offset:-2048
	global_load_dwordx4 v[242:245], v[246:247], off offset:-1024
	global_load_dwordx4 v[56:59], v[18:19], off
	s_add_u32 s34, s0, s40
	s_addc_u32 s35, s1, 0
	s_mulk_i32 s35, 0x4800
	s_mul_hi_u32 s40, s34, 0x4800
	v_readlane_b32 s68, v252, 4
	s_add_i32 s40, s40, s35
	s_mulk_i32 s34, 0x4800
	v_readlane_b32 s78, v252, 14
	v_readlane_b32 s79, v252, 15
	s_add_u32 s34, s78, s34
	s_addc_u32 s35, s79, s40
	s_cmp_lg_u32 s60, 0
	s_cselect_b64 s[44:45], -1, 0
	s_cmp_eq_u32 s60, 0
	v_readlane_b32 s69, v252, 5
	v_readlane_b32 s70, v252, 6
	v_readlane_b32 s71, v252, 7
	v_readlane_b32 s72, v252, 8
	v_readlane_b32 s73, v252, 9
	v_readlane_b32 s74, v252, 10
	v_readlane_b32 s75, v252, 11
	v_readlane_b32 s76, v252, 12
	v_readlane_b32 s77, v252, 13
	v_readlane_b32 s80, v252, 16
	v_readlane_b32 s81, v252, 17
	v_readlane_b32 s82, v252, 18
	v_readlane_b32 s83, v252, 19
	s_cbranch_scc1 .LBB0_807
	global_load_dwordx4 v[36:39], v[18:19], off offset:-4096
	s_mov_b64 s[40:41], 0
	s_waitcnt vmcnt(0)
	v_lshlrev_b32_e32 v40, 16, v36
	v_and_b32_e32 v34, 0xffff0000, v36
	v_lshlrev_b32_e32 v35, 16, v37
	v_and_b32_e32 v41, 0xffff0000, v37
	v_lshlrev_b32_e32 v36, 16, v38
	v_and_b32_e32 v26, 0xffff0000, v38
	v_lshlrev_b32_e32 v27, 16, v39
	v_and_b32_e32 v37, 0xffff0000, v39
	s_branch .LBB0_808
